# P5 tile start: hss loads kept early (renamed to v100-v117) but their waits+rsqrt arithmetic moved behind the 8 GEMM-prologue tile loads (vmcnt 11..8) so the two cold round trips overlap; dropped the v
# speedup vs baseline: 1.0014x; 1.0003x over previous
.LBB0_354:
	s_and_saveexec_b64 s[36:37], s[4:5]
	s_cbranch_execz .LBB0_356
	v_lshl_or_b32 v100, s34, 8, v0
	v_ashrrev_i32_e32 v101, 31, v100
	v_lshlrev_b64 v[100:101], 6, v[100:101]
	s_waitcnt vmcnt(0)
	v_lshl_add_u64 v[116:117], s[90:91], 0, v[100:101]
	global_load_dwordx4 v[100:103], v[116:117], off
	global_load_dwordx4 v[104:107], v[116:117], off offset:16
	global_load_dwordx4 v[108:111], v[116:117], off offset:32
	global_load_dwordx4 v[112:115], v[116:117], off offset:48
.LBB0_356:
	s_or_b64 exec, exec, s[36:37]
	v_mov_b32_e32 v2, v0
	s_mul_i32 s0, s34, 22
	v_lshlrev_b32_e32 v3, 4, v2
	v_bfe_i32 v2, v2, 27, 1
	v_lshrrev_b32_e32 v2, 22, v2
	v_add_u32_e32 v2, v3, v2
	v_ashrrev_i32_e32 v10, 10, v2
	v_mul_i32_i24_e32 v2, 0x400, v10
	v_sub_u32_e32 v2, v3, v2
	v_add_u32_e32 v4, 0x2000, v3
	v_lshrrev_b32_e32 v3, 4, v2
	v_bitop3_b32 v2, v3, v2, 32 bitop3:0x6c
	v_ashrrev_i32_e32 v5, 31, v2
	v_lshrrev_b32_e32 v5, 26, v5
	v_add_u32_e32 v5, v2, v5
	v_ashrrev_i32_e32 v12, 6, v5
	v_and_b32_e32 v5, 0xc0, v5
	v_sub_u32_e32 v2, v2, v5
	v_ashrrev_i16_sdwa v14, v153, sext(v2) dst_sel:DWORD dst_unused:UNUSED_PAD src0_sel:DWORD src1_sel:BYTE_0
	v_ashrrev_i32_e32 v2, 31, v4
	v_lshrrev_b32_e32 v2, 22, v2
	v_add_u32_e32 v2, v4, v2
	v_ashrrev_i32_e32 v11, 10, v2
	v_mul_i32_i24_e32 v2, 0x400, v11
	v_sub_u32_e32 v2, v4, v2
	s_sub_i32 s36, s54, s0
	v_lshrrev_b32_e32 v4, 4, v2
	s_ashr_i32 s37, s36, 31
	v_bitop3_b32 v2, v4, v2, 32 bitop3:0x6c
	s_lshl_b64 s[40:41], s[36:37], 19
	v_ashrrev_i32_e32 v5, 31, v2
	s_add_u32 s38, s42, s40
	v_lshrrev_b32_e32 v5, 26, v5
	s_addc_u32 s39, s43, s41
	s_ashr_i32 s35, s34, 31
	v_lshlrev_b32_e32 v3, 3, v10
	v_add_u32_e32 v5, v2, v5
	s_lshl_b64 s[46:47], s[34:35], 19
	v_and_b32_e32 v3, 0x3ffff0, v3
	v_lshlrev_b32_e32 v6, 5, v10
	v_lshlrev_b32_e32 v4, 3, v11
	v_ashrrev_i32_e32 v15, 6, v5
	v_and_b32_e32 v5, 0xc0, v5
	s_waitcnt lgkmcnt(0)
	s_add_u32 s48, s12, s46
	v_readfirstlane_b32 s0, v0
	v_add_u32_e32 v3, v12, v3
	v_and_b32_e32 v13, 32, v6
	v_and_b32_e32 v4, 0x3ffff0, v4
	v_lshlrev_b32_e32 v6, 5, v11
	v_sub_u32_e32 v2, v2, v5
	s_addc_u32 s49, s13, s47
	s_lshl_b32 s0, s0, 4
	v_add_u32_e32 v4, v15, v4
	v_and_b32_e32 v16, 32, v6
	v_ashrrev_i16_sdwa v17, v153, sext(v2) dst_sel:DWORD dst_unused:UNUSED_PAD src0_sel:DWORD src1_sel:BYTE_0
	v_lshl_or_b32 v2, v3, 10, v13
	v_lshl_or_b32 v3, v4, 10, v16
	s_and_b32 s35, s0, 0xfffffc00
	v_add_u32_sdwa v130, v2, sext(v14) dst_sel:DWORD dst_unused:UNUSED_PAD src0_sel:DWORD src1_sel:WORD_0
	v_add_u32_sdwa v132, v3, sext(v17) dst_sel:DWORD dst_unused:UNUSED_PAD src0_sel:DWORD src1_sel:WORD_0
	v_lshlrev_b64 v[18:19], 1, v[130:131]
	s_add_i32 s37, s35, 0x10000
	v_mov_b32_e32 v133, v131
	v_lshl_add_u64 v[2:3], s[48:49], 0, v[18:19]
	s_mov_b32 m0, s37
	v_lshlrev_b64 v[20:21], 1, v[132:133]
	s_add_i32 s55, s35, 0x12000
	global_load_lds_dwordx4 v[2:3], off
	v_lshl_add_u64 v[6:7], s[48:49], 0, v[20:21]
	s_mov_b32 m0, s55
	s_add_i32 s56, s35, 0x2000
	global_load_lds_dwordx4 v[6:7], off
	v_lshl_add_u64 v[8:9], s[38:39], 0, v[18:19]
	s_mov_b32 m0, s35
	s_add_u32 s0, s48, 0x40000
	global_load_lds_dwordx4 v[8:9], off
	v_lshl_add_u64 v[4:5], s[38:39], 0, v[20:21]
	s_mov_b32 m0, s56
	s_addc_u32 s1, s49, 0
	s_add_i32 s57, s35, 0x14000
	global_load_lds_dwordx4 v[4:5], off
	v_lshl_add_u64 v[22:23], s[0:1], 0, v[18:19]
	s_mov_b32 m0, s57
	s_add_i32 s58, s35, 0x16000
	global_load_lds_dwordx4 v[22:23], off
	v_lshl_add_u64 v[22:23], s[0:1], 0, v[20:21]
	s_add_u32 s0, s38, 0x40000
	s_mov_b32 m0, s58
	s_addc_u32 s1, s39, 0
	s_add_i32 s59, s35, 0x4000
	global_load_lds_dwordx4 v[22:23], off
	v_lshl_add_u64 v[18:19], s[0:1], 0, v[18:19]
	s_mov_b32 m0, s59
	s_add_i32 s60, s35, 0x6000
	global_load_lds_dwordx4 v[18:19], off
	v_lshl_add_u64 v[18:19], s[0:1], 0, v[20:21]
	s_mov_b32 m0, s60
	s_nop 0
	global_load_lds_dwordx4 v[18:19], off
	s_and_saveexec_b64 s[50:51], s[4:5]
	s_cbranch_execz .Lp5_srs_skip
	s_waitcnt vmcnt(11)
	v_mov_b32_e32 v116, v100
	s_waitcnt vmcnt(10)
	v_mov_b32_e32 v117, v104
	v_mov_b32_e32 v104, v101
	v_mov_b32_e32 v100, v102
	v_mov_b32_e32 v101, v106
	v_mov_b32_e32 v106, v103
	s_waitcnt vmcnt(9)
	v_mov_b32_e32 v102, v108
	s_waitcnt vmcnt(8)
	v_mov_b32_e32 v103, v112
	v_mov_b32_e32 v112, v109
	v_pk_add_f32 v[104:105], v[116:117], v[104:105]
	v_mov_b32_e32 v108, v110
	v_mov_b32_e32 v109, v114
	v_pk_add_f32 v[102:103], v[102:103], v[112:113]
	v_pk_add_f32 v[100:101], v[104:105], v[100:101]
	v_mov_b32_e32 v114, v111
	v_pk_add_f32 v[102:103], v[102:103], v[108:109]
	v_pk_add_f32 v[100:101], v[100:101], v[106:107]
	v_pk_add_f32 v[102:103], v[102:103], v[114:115]
	v_add_f32_e32 v100, v100, v101
	v_add_f32_e32 v100, v100, v102
	v_add_f32_e32 v100, v100, v103
	v_fmamk_f32 v100, v100, 0x3a800000, v144
	v_mul_f32_e32 v101, 0x4b800000, v100
	v_cmp_gt_f32_e32 vcc, s52, v100
	s_nop 1
	v_cndmask_b32_e32 v100, v100, v101, vcc
	v_rsq_f32_e32 v100, v100
	s_nop 0
	v_mul_f32_e32 v101, 0x45800000, v100
	v_cndmask_b32_e32 v100, v100, v101, vcc
	ds_write_b32 v1, v100
.Lp5_srs_skip:
	s_or_b64 exec, exec, s[50:51]
	s_and_saveexec_b64 s[50:51], s[6:7]
	s_cbranch_execz .LBB0_358
	s_barrier
